# P2 K-loop: removed compiler-inserted vmcnt(0) at loop top
# speedup vs baseline: 1.0001x; 1.0001x over previous
.LBB0_419:
	s_add_u32 s16, s14, 0xfffc0080
	s_addc_u32 s17, s15, -1
	s_add_i32 s23, 0, 0x10000
	s_cmp_eq_u32 s22, 12
	s_cselect_b32 s19, s97, s17
	s_cselect_b32 s18, s96, s16
	v_add_u32_e32 v8, s23, v170
	s_cselect_b32 s17, s95, s21
	s_cselect_b32 s16, s94, s20
	s_add_i32 s35, 0, 0x14000
	ds_read_b128 v[130:133], v8
	ds_read_b128 v[134:137], v8 offset:1024
	ds_read_b128 v[138:141], v8 offset:2048
	ds_read_b128 v[142:145], v8 offset:3072
	v_add_u32_e32 v8, s35, v170
	ds_read_b128 v[158:161], v8
	ds_read_b128 v[162:165], v8 offset:1024
	ds_read_b128 v[172:175], v8 offset:2048
	ds_read_b128 v[176:179], v8 offset:3072
	v_lshl_add_u64 v[166:167], s[14:15], 0, v[154:155]
	s_add_i32 m0, s62, 0xc000
	ds_read_b128 v[188:191], v171
	ds_read_b128 v[192:195], v171 offset:1024
	ds_read_b128 v[196:199], v171 offset:2048
	ds_read_b128 v[200:203], v171 offset:3072
	ds_read_b128 v[204:207], v171 offset:4096
	ds_read_b128 v[208:211], v171 offset:5120
	ds_read_b128 v[212:215], v171 offset:6144
	ds_read_b128 v[216:219], v171 offset:7168
	global_load_lds_dwordx4 v[166:167], off
	v_lshl_add_u64 v[166:167], s[14:15], 0, v[156:157]
	s_add_i32 m0, s62, 0xe000
	s_nop 0
	global_load_lds_dwordx4 v[166:167], off
	s_waitcnt vmcnt(8)
	s_waitcnt lgkmcnt(0)
	s_barrier
	s_setprio 1
	s_waitcnt lgkmcnt(0)
	v_mfma_f32_16x16x32_bf16 v[126:129], v[130:133], v[188:191], v[126:129]
	v_mfma_f32_16x16x32_bf16 v[118:121], v[138:141], v[188:191], v[118:121]
	v_mfma_f32_16x16x32_bf16 v[110:113], v[130:133], v[196:199], v[110:113]
	v_mfma_f32_16x16x32_bf16 v[102:105], v[138:141], v[196:199], v[102:105]
	v_mfma_f32_16x16x32_bf16 v[94:97], v[130:133], v[204:207], v[94:97]
	v_mfma_f32_16x16x32_bf16 v[86:89], v[138:141], v[204:207], v[86:89]
	v_mfma_f32_16x16x32_bf16 v[78:81], v[130:133], v[212:215], v[78:81]
	v_mfma_f32_16x16x32_bf16 v[70:73], v[138:141], v[212:215], v[70:73]
	v_mfma_f32_16x16x32_bf16 v[126:129], v[134:137], v[192:195], v[126:129]
	v_mfma_f32_16x16x32_bf16 v[118:121], v[142:145], v[192:195], v[118:121]
	v_mfma_f32_16x16x32_bf16 v[110:113], v[134:137], v[200:203], v[110:113]
	v_mfma_f32_16x16x32_bf16 v[102:105], v[142:145], v[200:203], v[102:105]
	v_mfma_f32_16x16x32_bf16 v[94:97], v[134:137], v[208:211], v[94:97]
	v_mfma_f32_16x16x32_bf16 v[86:89], v[142:145], v[208:211], v[86:89]
	v_mfma_f32_16x16x32_bf16 v[78:81], v[134:137], v[216:219], v[78:81]
	v_mfma_f32_16x16x32_bf16 v[70:73], v[142:145], v[216:219], v[70:73]
	s_setprio 0
	s_setprio 1
	v_mfma_f32_16x16x32_bf16 v[122:125], v[158:161], v[188:191], v[122:125]
	v_mfma_f32_16x16x32_bf16 v[114:117], v[172:175], v[188:191], v[114:117]
	v_mfma_f32_16x16x32_bf16 v[106:109], v[158:161], v[196:199], v[106:109]
	v_mfma_f32_16x16x32_bf16 v[98:101], v[172:175], v[196:199], v[98:101]
	v_mfma_f32_16x16x32_bf16 v[90:93], v[158:161], v[204:207], v[90:93]
	v_mfma_f32_16x16x32_bf16 v[82:85], v[172:175], v[204:207], v[82:85]
	v_mfma_f32_16x16x32_bf16 v[74:77], v[158:161], v[212:215], v[74:77]
	v_mfma_f32_16x16x32_bf16 v[66:69], v[172:175], v[212:215], v[66:69]
	v_mfma_f32_16x16x32_bf16 v[122:125], v[162:165], v[192:195], v[122:125]
	v_mfma_f32_16x16x32_bf16 v[114:117], v[176:179], v[192:195], v[114:117]
	v_mfma_f32_16x16x32_bf16 v[106:109], v[162:165], v[200:203], v[106:109]
	v_mfma_f32_16x16x32_bf16 v[98:101], v[176:179], v[200:203], v[98:101]
	v_mfma_f32_16x16x32_bf16 v[90:93], v[162:165], v[208:211], v[90:93]
	v_mfma_f32_16x16x32_bf16 v[82:85], v[176:179], v[208:211], v[82:85]
	v_mfma_f32_16x16x32_bf16 v[74:77], v[162:165], v[216:219], v[74:77]
	v_mfma_f32_16x16x32_bf16 v[66:69], v[176:179], v[216:219], v[66:69]
	s_setprio 0
	s_barrier
	s_add_i32 s23, s23, s76
	v_lshl_add_u64 v[166:167], s[16:17], 0, v[148:149]
	s_mov_b32 m0, s23
	ds_read_b128 v[188:191], v171 offset:16384
	ds_read_b128 v[192:195], v171 offset:17408
	ds_read_b128 v[196:199], v171 offset:18432
	ds_read_b128 v[200:203], v171 offset:19456
	ds_read_b128 v[204:207], v171 offset:20480
	ds_read_b128 v[208:211], v171 offset:21504
	ds_read_b128 v[212:215], v171 offset:22528
	ds_read_b128 v[216:219], v171 offset:23552
	global_load_lds_dwordx4 v[166:167], off
	s_add_i32 m0, s23, 0x2000
	s_add_u32 s24, s16, 0x40000
	v_lshl_add_u64 v[220:221], s[16:17], 0, v[152:153]
	s_addc_u32 s25, s17, 0
	s_add_i32 s23, s35, s76
	global_load_lds_dwordx4 v[220:221], off
	v_lshl_add_u64 v[222:223], s[24:25], 0, v[148:149]
	s_mov_b32 m0, s23
	v_lshl_add_u64 v[224:225], s[18:19], 0, v[150:151]
	global_load_lds_dwordx4 v[222:223], off
	v_lshl_add_u64 v[222:223], s[24:25], 0, v[152:153]
	s_add_i32 m0, s23, 0x2000
	s_nop 0
	global_load_lds_dwordx4 v[222:223], off
	v_lshl_add_u64 v[222:223], s[18:19], 0, v[146:147]
	s_mov_b32 m0, s62
	s_nop 0
	global_load_lds_dwordx4 v[222:223], off
	s_mov_b32 m0, s11
	s_nop 0
	global_load_lds_dwordx4 v[224:225], off
	s_waitcnt vmcnt(8)
	s_waitcnt lgkmcnt(0)
	s_barrier
	s_setprio 1
	s_waitcnt lgkmcnt(0)
	v_mfma_f32_16x16x32_bf16 v[62:65], v[130:133], v[188:191], v[62:65]
	v_mfma_f32_16x16x32_bf16 v[54:57], v[138:141], v[188:191], v[54:57]
	v_mfma_f32_16x16x32_bf16 v[46:49], v[130:133], v[196:199], v[46:49]
	v_mfma_f32_16x16x32_bf16 v[38:41], v[138:141], v[196:199], v[38:41]
	v_mfma_f32_16x16x32_bf16 v[30:33], v[130:133], v[204:207], v[30:33]
	v_mfma_f32_16x16x32_bf16 v[22:25], v[138:141], v[204:207], v[22:25]
	v_mfma_f32_16x16x32_bf16 v[14:17], v[130:133], v[212:215], v[14:17]
	v_mfma_f32_16x16x32_bf16 v[4:7], v[138:141], v[212:215], v[4:7]
	v_mfma_f32_16x16x32_bf16 v[62:65], v[134:137], v[192:195], v[62:65]
	v_mfma_f32_16x16x32_bf16 v[54:57], v[142:145], v[192:195], v[54:57]
	v_mfma_f32_16x16x32_bf16 v[46:49], v[134:137], v[200:203], v[46:49]
	v_mfma_f32_16x16x32_bf16 v[38:41], v[142:145], v[200:203], v[38:41]
	v_mfma_f32_16x16x32_bf16 v[30:33], v[134:137], v[208:211], v[30:33]
	v_mfma_f32_16x16x32_bf16 v[22:25], v[142:145], v[208:211], v[22:25]
	v_mfma_f32_16x16x32_bf16 v[14:17], v[134:137], v[216:219], v[14:17]
	v_mfma_f32_16x16x32_bf16 v[4:7], v[142:145], v[216:219], v[4:7]
	s_setprio 0
	s_setprio 1
	v_mfma_f32_16x16x32_bf16 v[58:61], v[158:161], v[188:191], v[58:61]
	v_mfma_f32_16x16x32_bf16 v[50:53], v[172:175], v[188:191], v[50:53]
	v_mfma_f32_16x16x32_bf16 v[42:45], v[158:161], v[196:199], v[42:45]
	v_mfma_f32_16x16x32_bf16 v[34:37], v[172:175], v[196:199], v[34:37]
	v_mfma_f32_16x16x32_bf16 v[26:29], v[158:161], v[204:207], v[26:29]
	v_mfma_f32_16x16x32_bf16 v[18:21], v[172:175], v[204:207], v[18:21]
	v_mfma_f32_16x16x32_bf16 v[10:13], v[158:161], v[212:215], v[10:13]
	v_mfma_f32_16x16x32_bf16 v[0:3], v[172:175], v[212:215], v[0:3]
	v_mfma_f32_16x16x32_bf16 v[58:61], v[162:165], v[192:195], v[58:61]
	v_mfma_f32_16x16x32_bf16 v[50:53], v[176:179], v[192:195], v[50:53]
	v_mfma_f32_16x16x32_bf16 v[42:45], v[162:165], v[200:203], v[42:45]
	v_mfma_f32_16x16x32_bf16 v[34:37], v[176:179], v[200:203], v[34:37]
	v_mfma_f32_16x16x32_bf16 v[26:29], v[162:165], v[208:211], v[26:29]
	v_mfma_f32_16x16x32_bf16 v[18:21], v[176:179], v[208:211], v[18:21]
	v_mfma_f32_16x16x32_bf16 v[10:13], v[162:165], v[216:219], v[10:13]
	v_mfma_f32_16x16x32_bf16 v[0:3], v[176:179], v[216:219], v[0:3]
	s_setprio 0
	s_barrier
	s_add_i32 s23, 0, 0x18000
	v_add_u32_e32 v8, s23, v170
	s_add_i32 s24, 0, 0x1c000
	ds_read_b128 v[130:133], v8
	ds_read_b128 v[134:137], v8 offset:1024
	ds_read_b128 v[138:141], v8 offset:2048
	ds_read_b128 v[142:145], v8 offset:3072
	v_add_u32_e32 v8, s24, v170
	ds_read_b128 v[158:161], v8
	ds_read_b128 v[162:165], v8 offset:1024
	ds_read_b128 v[172:175], v8 offset:2048
	ds_read_b128 v[176:179], v8 offset:3072
	s_add_u32 s18, s18, 0x40000
	s_addc_u32 s19, s19, 0
	s_mov_b32 m0, s8
	v_lshl_add_u64 v[226:227], s[18:19], 0, v[146:147]
	ds_read_b128 v[188:191], v171 offset:32768
	ds_read_b128 v[192:195], v171 offset:33792
	ds_read_b128 v[196:199], v171 offset:34816
	ds_read_b128 v[200:203], v171 offset:35840
	ds_read_b128 v[204:207], v171 offset:36864
	ds_read_b128 v[208:211], v171 offset:37888
	ds_read_b128 v[212:215], v171 offset:38912
	ds_read_b128 v[216:219], v171 offset:39936
	global_load_lds_dwordx4 v[226:227], off
	v_lshl_add_u64 v[226:227], s[18:19], 0, v[150:151]
	s_mov_b32 m0, s9
	s_nop 0
	global_load_lds_dwordx4 v[226:227], off
	s_waitcnt vmcnt(8)
	s_waitcnt lgkmcnt(0)
	s_barrier
	s_setprio 1
	s_waitcnt lgkmcnt(0)
	v_mfma_f32_16x16x32_bf16 v[126:129], v[130:133], v[188:191], v[126:129]
	v_mfma_f32_16x16x32_bf16 v[118:121], v[138:141], v[188:191], v[118:121]
	v_mfma_f32_16x16x32_bf16 v[110:113], v[130:133], v[196:199], v[110:113]
	v_mfma_f32_16x16x32_bf16 v[102:105], v[138:141], v[196:199], v[102:105]
	v_mfma_f32_16x16x32_bf16 v[94:97], v[130:133], v[204:207], v[94:97]
	v_mfma_f32_16x16x32_bf16 v[86:89], v[138:141], v[204:207], v[86:89]
	v_mfma_f32_16x16x32_bf16 v[78:81], v[130:133], v[212:215], v[78:81]
	v_mfma_f32_16x16x32_bf16 v[70:73], v[138:141], v[212:215], v[70:73]
	v_mfma_f32_16x16x32_bf16 v[126:129], v[134:137], v[192:195], v[126:129]
	v_mfma_f32_16x16x32_bf16 v[118:121], v[142:145], v[192:195], v[118:121]
	v_mfma_f32_16x16x32_bf16 v[110:113], v[134:137], v[200:203], v[110:113]
	v_mfma_f32_16x16x32_bf16 v[102:105], v[142:145], v[200:203], v[102:105]
	v_mfma_f32_16x16x32_bf16 v[94:97], v[134:137], v[208:211], v[94:97]
	v_mfma_f32_16x16x32_bf16 v[86:89], v[142:145], v[208:211], v[86:89]
	v_mfma_f32_16x16x32_bf16 v[78:81], v[134:137], v[216:219], v[78:81]
	v_mfma_f32_16x16x32_bf16 v[70:73], v[142:145], v[216:219], v[70:73]
	s_setprio 0
	s_setprio 1
	v_mfma_f32_16x16x32_bf16 v[122:125], v[158:161], v[188:191], v[122:125]
	v_mfma_f32_16x16x32_bf16 v[114:117], v[172:175], v[188:191], v[114:117]
	v_mfma_f32_16x16x32_bf16 v[106:109], v[158:161], v[196:199], v[106:109]
	v_mfma_f32_16x16x32_bf16 v[98:101], v[172:175], v[196:199], v[98:101]
	v_mfma_f32_16x16x32_bf16 v[90:93], v[158:161], v[204:207], v[90:93]
	v_mfma_f32_16x16x32_bf16 v[82:85], v[172:175], v[204:207], v[82:85]
	v_mfma_f32_16x16x32_bf16 v[74:77], v[158:161], v[212:215], v[74:77]
	v_mfma_f32_16x16x32_bf16 v[66:69], v[172:175], v[212:215], v[66:69]
	v_mfma_f32_16x16x32_bf16 v[122:125], v[162:165], v[192:195], v[122:125]
	v_mfma_f32_16x16x32_bf16 v[114:117], v[176:179], v[192:195], v[114:117]
	v_mfma_f32_16x16x32_bf16 v[106:109], v[162:165], v[200:203], v[106:109]
	v_mfma_f32_16x16x32_bf16 v[98:101], v[176:179], v[200:203], v[98:101]
	v_mfma_f32_16x16x32_bf16 v[90:93], v[162:165], v[208:211], v[90:93]
	v_mfma_f32_16x16x32_bf16 v[82:85], v[176:179], v[208:211], v[82:85]
	v_mfma_f32_16x16x32_bf16 v[74:77], v[162:165], v[216:219], v[74:77]
	v_mfma_f32_16x16x32_bf16 v[66:69], v[176:179], v[216:219], v[66:69]
	s_setprio 0
	s_barrier
	s_add_i32 s18, s23, s76
	v_lshl_add_u64 v[166:167], v[166:167], 0, s[86:87]
	s_mov_b32 m0, s18
	ds_read_b128 v[188:191], v171 offset:49152
	ds_read_b128 v[192:195], v171 offset:50176
	ds_read_b128 v[196:199], v171 offset:51200
	ds_read_b128 v[200:203], v171 offset:52224
	ds_read_b128 v[204:207], v171 offset:53248
	ds_read_b128 v[208:211], v171 offset:54272
	ds_read_b128 v[212:215], v171 offset:55296
	ds_read_b128 v[216:219], v171 offset:56320
	global_load_lds_dwordx4 v[166:167], off
	s_add_i32 m0, s18, 0x2000
	s_add_u32 s16, s16, 0x40080
	v_lshl_add_u64 v[166:167], v[220:221], 0, s[86:87]
	s_addc_u32 s17, s17, 0
	s_add_i32 s18, s24, s76
	global_load_lds_dwordx4 v[166:167], off
	v_lshl_add_u64 v[166:167], s[16:17], 0, v[148:149]
	s_mov_b32 m0, s18
	s_nop 0
	global_load_lds_dwordx4 v[166:167], off
	v_lshl_add_u64 v[166:167], s[16:17], 0, v[152:153]
	s_add_i32 m0, s18, 0x2000
	s_nop 0
	global_load_lds_dwordx4 v[166:167], off
	v_lshl_add_u64 v[166:167], v[222:223], 0, s[86:87]
	s_mov_b32 m0, s79
	s_nop 0
	global_load_lds_dwordx4 v[166:167], off
	v_lshl_add_u64 v[166:167], v[224:225], 0, s[86:87]
	s_mov_b32 m0, s6
	s_nop 0
	global_load_lds_dwordx4 v[166:167], off
	s_waitcnt vmcnt(8)
	s_waitcnt lgkmcnt(0)
	s_barrier
	s_setprio 1
	s_waitcnt lgkmcnt(0)
	v_mfma_f32_16x16x32_bf16 v[62:65], v[130:133], v[188:191], v[62:65]
	v_mfma_f32_16x16x32_bf16 v[54:57], v[138:141], v[188:191], v[54:57]
	v_mfma_f32_16x16x32_bf16 v[46:49], v[130:133], v[196:199], v[46:49]
	v_mfma_f32_16x16x32_bf16 v[38:41], v[138:141], v[196:199], v[38:41]
	v_mfma_f32_16x16x32_bf16 v[30:33], v[130:133], v[204:207], v[30:33]
	v_mfma_f32_16x16x32_bf16 v[22:25], v[138:141], v[204:207], v[22:25]
	v_mfma_f32_16x16x32_bf16 v[14:17], v[130:133], v[212:215], v[14:17]
	v_mfma_f32_16x16x32_bf16 v[4:7], v[138:141], v[212:215], v[4:7]
	v_mfma_f32_16x16x32_bf16 v[62:65], v[134:137], v[192:195], v[62:65]
	v_mfma_f32_16x16x32_bf16 v[54:57], v[142:145], v[192:195], v[54:57]
	v_mfma_f32_16x16x32_bf16 v[46:49], v[134:137], v[200:203], v[46:49]
	v_mfma_f32_16x16x32_bf16 v[38:41], v[142:145], v[200:203], v[38:41]
	v_mfma_f32_16x16x32_bf16 v[30:33], v[134:137], v[208:211], v[30:33]
	v_mfma_f32_16x16x32_bf16 v[22:25], v[142:145], v[208:211], v[22:25]
	v_mfma_f32_16x16x32_bf16 v[14:17], v[134:137], v[216:219], v[14:17]
	v_mfma_f32_16x16x32_bf16 v[4:7], v[142:145], v[216:219], v[4:7]
	s_setprio 0
	s_setprio 1
	v_mfma_f32_16x16x32_bf16 v[58:61], v[158:161], v[188:191], v[58:61]
	v_mfma_f32_16x16x32_bf16 v[50:53], v[172:175], v[188:191], v[50:53]
	v_mfma_f32_16x16x32_bf16 v[42:45], v[158:161], v[196:199], v[42:45]
	v_mfma_f32_16x16x32_bf16 v[34:37], v[172:175], v[196:199], v[34:37]
	v_mfma_f32_16x16x32_bf16 v[26:29], v[158:161], v[204:207], v[26:29]
	v_mfma_f32_16x16x32_bf16 v[18:21], v[172:175], v[204:207], v[18:21]
	v_mfma_f32_16x16x32_bf16 v[10:13], v[158:161], v[212:215], v[10:13]
	v_mfma_f32_16x16x32_bf16 v[0:3], v[172:175], v[212:215], v[0:3]
	v_mfma_f32_16x16x32_bf16 v[58:61], v[162:165], v[192:195], v[58:61]
	v_mfma_f32_16x16x32_bf16 v[50:53], v[176:179], v[192:195], v[50:53]
	v_mfma_f32_16x16x32_bf16 v[42:45], v[162:165], v[200:203], v[42:45]
	v_mfma_f32_16x16x32_bf16 v[34:37], v[176:179], v[200:203], v[34:37]
	v_mfma_f32_16x16x32_bf16 v[26:29], v[162:165], v[208:211], v[26:29]
	v_mfma_f32_16x16x32_bf16 v[18:21], v[176:179], v[208:211], v[18:21]
	v_mfma_f32_16x16x32_bf16 v[10:13], v[162:165], v[216:219], v[10:13]
	v_mfma_f32_16x16x32_bf16 v[0:3], v[176:179], v[216:219], v[0:3]
	s_setprio 0
	s_barrier
	s_add_i32 s22, s22, 2
	s_add_u32 s14, s14, 0x100
	s_addc_u32 s15, s15, 0
	s_add_u32 s20, s20, 0x100
	s_addc_u32 s21, s21, 0
	s_cmp_gt_u32 s22, 13
	s_cbranch_scc0 .LBB0_419
	s_and_b64 vcc, exec, s[4:5]
	s_cbranch_vccz .LBB0_422
	s_barrier
